# code placement: attention-phase loop heads (selected, window, SWA, pass 1/2, top-k) also aligned to 64 bytes
# baseline (speedup 1.0000x reference)
.LBB0_247:
	s_cmp_gt_i32 s18, -1
	s_cbranch_scc0 .LBB0_263
	v_lshlrev_b64 v[18:19], 1, v[126:127]
	v_lshlrev_b32_e32 v0, 2, v144
	v_mov_b32_e32 v20, v1
	v_mov_b32_e32 v21, v1
	v_lshl_add_u64 v[160:161], s[42:43], 0, v[18:19]
	v_lshl_add_u64 v[162:163], s[44:45], 0, v[18:19]
	v_or_b32_e32 v164, 16, v144
	v_sub_u32_e32 v145, v224, v0
	v_mov_b32_e32 v0, v1
	v_mov_b32_e32 v149, v148
	v_mov_b32_e32 v18, v1
	v_mov_b32_e32 v19, v1
	v_mov_b64_e32 v[24:25], v[20:21]
	v_mov_b64_e32 v[28:29], v[20:21]
	v_mov_b64_e32 v[32:33], v[20:21]
	v_mov_b64_e32 v[36:37], v[20:21]
	v_mov_b64_e32 v[40:41], v[20:21]
	v_mov_b64_e32 v[44:45], v[20:21]
	v_mov_b64_e32 v[48:49], v[20:21]
	s_add_i32 s19, s5, 0xffffff9f
	v_mov_b32_e32 v123, v144
	v_mov_b32_e32 v125, v164
	s_mov_b32 s23, 0
	v_mov_b64_e32 v[22:23], v[18:19]
	v_mov_b64_e32 v[26:27], v[18:19]
	v_mov_b64_e32 v[30:31], v[18:19]
	v_mov_b64_e32 v[34:35], v[18:19]
	v_mov_b64_e32 v[38:39], v[18:19]
	v_mov_b64_e32 v[42:43], v[18:19]
	v_mov_b64_e32 v[166:167], v[148:149]
	v_mov_b64_e32 v[158:159], v[0:1]
	v_mov_b64_e32 v[46:47], v[18:19]
	s_waitcnt vmcnt(0)
	.p2alignl 6, 3212836864

.LBB0_254:
	s_mov_b32 s44, 1
	s_mov_b64 s[76:77], 0
	s_cbranch_execnz .LBB0_261
	.p2alignl 6, 3212836864

.LBB0_279:
	s_cmp_gt_i32 s14, -1
	s_cbranch_scc0 .LBB0_230
	v_lshlrev_b32_e32 v0, 2, v144
	v_mov_b32_e32 v20, v1
	v_mov_b32_e32 v21, v1
	v_sub_u32_e32 v145, v227, v0
	v_mov_b32_e32 v149, v148
	v_mov_b32_e32 v0, v1
	v_mov_b32_e32 v18, v1
	v_mov_b32_e32 v19, v1
	v_mov_b64_e32 v[24:25], v[20:21]
	v_mov_b64_e32 v[28:29], v[20:21]
	v_mov_b64_e32 v[32:33], v[20:21]
	v_mov_b64_e32 v[36:37], v[20:21]
	v_mov_b64_e32 v[40:41], v[20:21]
	v_mov_b64_e32 v[44:45], v[20:21]
	v_mov_b64_e32 v[48:49], v[20:21]
	s_or_b32 s18, s4, 31
	v_mov_b32_e32 v123, v144
	v_mov_b32_e32 v125, v158
	s_mov_b32 s19, 0
	v_mov_b64_e32 v[22:23], v[18:19]
	v_mov_b64_e32 v[26:27], v[18:19]
	v_mov_b64_e32 v[30:31], v[18:19]
	v_mov_b64_e32 v[34:35], v[18:19]
	v_mov_b64_e32 v[38:39], v[18:19]
	v_mov_b64_e32 v[42:43], v[18:19]
	v_mov_b64_e32 v[160:161], v[0:1]
	v_mov_b64_e32 v[166:167], v[148:149]
	v_mov_b64_e32 v[46:47], v[18:19]
	.p2alignl 6, 3212836864

.LBB0_286:
	s_mov_b32 s25, 1
	s_mov_b64 s[72:73], 0
	s_cbranch_execnz .LBB0_293
	.p2alignl 6, 3212836864

.LBB0_352:
	s_add_i32 s8, s15, s2
	s_mov_b64 s[6:7], 0x40000
	s_add_i32 m0, s8, 0x4000
	v_lshl_add_u64 v[4:5], v[2:3], 0, s[6:7]
	global_load_lds_dwordx4 v[2:3], off
	s_add_i32 m0, s8, 0xc000
	s_addk_i32 s2, 0x2000
	global_load_lds_dwordx4 v[4:5], off
	s_mov_b64 s[6:7], 0x2000
	s_cmp_eq_u32 s5, s2
	v_lshl_add_u64 v[2:3], v[2:3], 0, s[6:7]
	s_cbranch_scc0 .LBB0_352
	s_lshl_b32 s22, s4, 12
	s_lshl_b32 s14, s0, 6
	v_readlane_b32 s2, v255, 20
	s_ashr_i32 s23, s22, 31
	s_add_i32 s2, s14, s2
	s_lshl_b64 s[4:5], s[22:23], 13
	v_readlane_b32 s6, v255, 18
	v_lshl_or_b32 v145, s1, 2, v191
	v_readlane_b32 s7, v255, 19
	s_add_u32 s20, s6, s4
	v_or_b32_e32 v140, s2, v122
	s_addc_u32 s21, s7, s5
	v_lshlrev_b32_e32 v0, 7, v145
	v_or_b32_e32 v142, 4, v140
	v_lshl_add_u64 v[2:3], s[20:21], 0, v[0:1]
	v_mov_b32_e32 v137, v1
	v_ashrrev_i32_e32 v141, 31, v140
	v_ashrrev_i32_e32 v143, 31, v142
	v_lshl_add_u64 v[10:11], v[2:3], 0, v[136:137]
	v_lshlrev_b64 v[2:3], 13, v[140:141]
	v_lshlrev_b64 v[12:13], 13, v[142:143]
	v_lshl_add_u64 v[6:7], v[10:11], 0, v[2:3]
	v_lshl_add_u64 v[14:15], v[10:11], 0, v[12:13]
	global_load_dwordx4 v[2:5], v[6:7], off
	s_nop 0
	global_load_dwordx4 v[6:9], v[6:7], off offset:64
	s_nop 0
	global_load_dwordx4 v[10:13], v[14:15], off
	s_nop 0
	global_load_dwordx4 v[14:17], v[14:15], off offset:64
	s_waitcnt vmcnt(0)
	ds_write_b128 v192, v[24:27]
	ds_write_b128 v192, v[28:31] offset:8192
	s_sub_i32 s5, s2, 31
	v_mov_b32_e32 v20, v1
	v_mov_b32_e32 v21, v1
	s_or_b32 s4, s2, 7
	v_add_u32_e32 v137, s5, v123
	v_add_u32_e32 v144, s5, v122
	v_lshlrev_b32_e32 v143, 2, v140
	s_lshl_b32 s13, s16, 10
	v_mov_b32_e32 v0, v1
	v_mov_b32_e32 v18, v1
	v_mov_b32_e32 v19, v1
	v_mov_b64_e32 v[24:25], v[20:21]
	v_mov_b64_e32 v[28:29], v[20:21]
	v_mov_b64_e32 v[32:33], v[20:21]
	v_mov_b64_e32 v[36:37], v[20:21]
	v_mov_b64_e32 v[40:41], v[20:21]
	v_mov_b64_e32 v[44:45], v[20:21]
	v_mov_b64_e32 v[48:49], v[20:21]
	v_lshlrev_b32_e32 v138, 6, v145
	s_add_i32 s23, s2, 0xfffffbf1
	s_sub_i32 s12, 0x41f, s4
	v_mov_b32_e32 v158, v144
	v_mov_b32_e32 v139, v144
	v_mov_b32_e32 v160, v137
	v_mov_b32_e32 v141, v137
	v_sub_u32_e32 v149, v217, v143
	s_addk_i32 s13, 0x400
	v_mov_b32_e32 v238, 0xf149f2ca
	s_mov_b32 s18, 0
	v_mov_b32_e32 v159, v197
	s_mov_b32 s19, 0
	v_mov_b32_e32 v230, v223
	v_mov_b32_e32 v231, v222
	v_mov_b32_e32 v232, v221
	v_mov_b32_e32 v233, v220
	v_mov_b32_e32 v234, v219
	v_mov_b32_e32 v235, v218
	v_mov_b64_e32 v[22:23], v[18:19]
	v_mov_b64_e32 v[26:27], v[18:19]
	v_mov_b64_e32 v[30:31], v[18:19]
	v_mov_b64_e32 v[34:35], v[18:19]
	v_mov_b64_e32 v[38:39], v[18:19]
	v_mov_b64_e32 v[42:43], v[18:19]
	v_mov_b64_e32 v[46:47], v[18:19]
	s_mov_b32 s4, 0
	v_mov_b64_e32 v[162:163], v[0:1]
	v_mov_b32_e32 v0, 0xf149f2ca
	s_waitcnt vmcnt(0) lgkmcnt(0)
	s_barrier
	.p2alignl 6, 3212836864

.LBB0_365:
	s_add_i32 s4, s4, 1
	v_add_u32_e32 v39, 0x1000, v39
	v_add_u32_e32 v40, 0x1000, v40
	v_add_u32_e32 v45, 64, v45
	v_add_u32_e32 v44, 0x2000, v44
	v_add_u32_e32 v43, 0x2000, v43
	v_add_u32_e32 v42, 64, v42
	s_cmp_eq_u32 s4, 4
	v_add_u32_e32 v41, 0xfffffc00, v41
	s_cbranch_scc1 .LBB0_402
	.p2alignl 6, 3212836864

.LBB0_403:
	s_or_b64 exec, exec, s[6:7]
	s_add_i32 s0, s0, 8
	s_cmp_eq_u32 s0, 64
	v_add_u32_e32 v0, 0x100, v0
	s_cbranch_scc1 .LBB0_408
	.p2alignl 6, 3212836864

.LBB0_411:
	s_andn2_b64 vcc, exec, s[10:11]
	s_cbranch_vccnz .LBB0_349
	v_mov_b32_e32 v20, v1
	v_mov_b32_e32 v21, v1
	v_mov_b32_e32 v0, v1
	v_mov_b32_e32 v149, v148
	v_mov_b32_e32 v18, v1
	v_mov_b32_e32 v19, v1
	v_mov_b64_e32 v[24:25], v[20:21]
	v_mov_b64_e32 v[28:29], v[20:21]
	v_mov_b64_e32 v[32:33], v[20:21]
	v_mov_b64_e32 v[52:53], v[20:21]
	v_mov_b64_e32 v[44:45], v[20:21]
	v_mov_b64_e32 v[48:49], v[20:21]
	v_mov_b64_e32 v[36:37], v[20:21]
	s_add_i32 s1, s2, 0xfffffceb
	s_add_i32 s4, s2, 0xfffffc07
	s_mov_b32 s5, 0
	v_mov_b64_e32 v[22:23], v[18:19]
	v_mov_b64_e32 v[26:27], v[18:19]
	v_mov_b64_e32 v[30:31], v[18:19]
	v_mov_b64_e32 v[50:51], v[18:19]
	v_mov_b64_e32 v[42:43], v[18:19]
	v_mov_b64_e32 v[46:47], v[18:19]
	v_mov_b64_e32 v[34:35], v[18:19]
	s_mov_b32 s12, s0
	v_mov_b64_e32 v[160:161], v[148:149]
	v_mov_b64_e32 v[144:145], v[0:1]
	.p2alignl 6, 3212836864

.LBB0_418:
	s_mov_b32 s13, 1
	s_mov_b64 s[20:21], 0
	s_cbranch_execnz .LBB0_449
	.p2alignl 6, 3212836864
